# attention: key-permuted + XOR-swizzled V^T/K LDS tiles (conflict-free ds_read_b128 instead of 2-way-conflicted ds_read2_b64), 3-deep K-fragment prefetch in QK^T
# speedup vs baseline: 1.0356x; 1.0234x over previous
; DEV int get_tid() { int t = threadIdx.x; asm volatile("" : "+v"(t)); return t; }
; DEV void attn_item(const Params& p, int layer, int h, int qb, float lam, bf16_t* lds) {
;     ...
;   const int tid = get_tid(), lane = tid & 63, wave = tid >> 6;
;   const int lr = lane & 15, lg = lane >> 4;
;   const int grp = wave >> 2, wq = wave & 3;
;   const int t0 = qb * 128;
;   const int lrow = tid >> 4, lc8 = (tid & 15) * 8;
;   const bf16_t* gq = DQ + (size_t)(t0 + wq * 32 + lr) * 1024 + h * 128 + grp * 64 + lg * 8;
;   const bf16x8 a00 = *(const bf16x8*)(gq);
;   const bf16x8 a01 = *(const bf16x8*)(gq + 32);
;   const bf16x8 a10 = *(const bf16x8*)(gq + (size_t)16 * 1024);
;   const bf16x8 a11 = *(const bf16x8*)(gq + (size_t)16 * 1024 + 32);
;   f32x4 o[2][8];
; #pragma unroll
;   for (int i = 0; i < 2; i++)
; #pragma unroll
;     for (int j = 0; j < 8; j++) o[i][j] = (f32x4){0.f, 0.f, 0.f, 0.f};
;   float mrun0 = -1e30f, mrun1 = -1e30f, lrun0 = 0.f, lrun1 = 0.f;
;   u32x4 rk0, rk1, rk2, rk3, rv0, rv1, rv2, rv3;
;   const unsigned ko = (unsigned)(lrow * 1024 + h * 128 + lc8);
;   const unsigned vo = (unsigned)((h * 128 + lrow) * LT + lc8);
;     ...
;   ALOAD(0)
;   const int qrow0 = t0 + wq * 32 + lr;
;   __syncthreads();
;   ASTORE(KV + lrow * PS + lc8)
;   {
;     const int kb1 = qb > 0 ? 1 : 0;
;     ALOAD(kb1)
;   }
;   __syncthreads();
.LBB0_706:
	v_mov_b32_e32 v224, v181
	s_ashr_i32 s0, s2, 3
	s_sub_i32 s76, 64, s0
	v_lshrrev_b32_e32 v2, 1, v224
	v_and_b32_e32 v226, 0x60, v2
	v_and_b32_e32 v222, 15, v224
	v_lshlrev_b32_e32 v0, 3, v224
	v_lshl_or_b32 v223, s76, 7, v226
	s_lshl_b32 s1, s2, 7
	v_ashrrev_i32_e32 v84, 4, v224
	v_or_b32_e32 v184, v223, v222
	v_mov_b32_e32 v185, v1
	v_readlane_b32 s6, v254, 55
	s_and_b32 s75, s1, 0x380
	v_and_b32_e32 v85, 0x78, v0
	v_lshlrev_b32_e32 v0, 10, v84
	v_ashrrev_i32_e32 v225, 8, v224
	v_lshlrev_b64 v[2:3], 11, v[184:185]
	v_readlane_b32 s7, v254, 56
	v_or3_b32 v186, v0, s75, v85
	v_add_u32_e32 v0, s75, v84
	s_movk_i32 s1, 0x2080
	v_lshl_add_u64 v[2:3], s[6:7], 0, v[2:3]
	s_lshl_b32 s82, s75, 1
	v_lshlrev_b32_e32 v4, 6, v225
	v_mul_lo_u32 v0, v0, s1
	v_lshl_add_u64 v[2:3], v[2:3], 0, s[82:83]
	v_ashrrev_i32_e32 v5, 31, v4
	v_or_b32_e32 v188, v0, v85
	v_mov_b32_e32 v187, v1
	v_add_u32_e32 v0, 0x8000, v186
	v_lshl_add_u64 v[2:3], v[4:5], 1, v[2:3]
	v_lshl_add_u64 v[4:5], v[186:187], 1, s[78:79]
	v_lshl_add_u64 v[6:7], v[0:1], 1, s[78:79]
	v_add_u32_e32 v0, 0x10000, v186
	global_load_dwordx4 v[52:55], v[4:5], off
	global_load_dwordx4 v[56:59], v[6:7], off
	v_lshl_add_u64 v[4:5], v[0:1], 1, s[78:79]
	v_add_u32_e32 v0, 0x18000, v186
	v_lshl_add_u64 v[6:7], v[0:1], 1, s[78:79]
	v_mov_b32_e32 v189, v1
	v_add_u32_e32 v0, 0x41000, v188
	global_load_dwordx4 v[60:63], v[4:5], off
	global_load_dwordx4 v[64:67], v[6:7], off
	v_lshl_add_u64 v[4:5], v[188:189], 1, s[70:71]
	v_lshl_add_u64 v[6:7], v[0:1], 1, s[70:71]
	v_add_u32_e32 v0, 0x82000, v188
	v_and_b32_e32 v182, 48, v224
	v_mov_b32_e32 v183, v1
	global_load_dwordx4 v[68:71], v[4:5], off
	global_load_dwordx4 v[72:75], v[6:7], off
	v_lshl_add_u64 v[4:5], v[0:1], 1, s[70:71]
	v_add_u32_e32 v0, 0xc3000, v188
	global_load_dwordx4 v[76:79], v[4:5], off
	v_lshl_add_u64 v[4:5], v[0:1], 1, s[70:71]
	v_lshl_add_u64 v[2:3], v[2:3], 0, v[182:183]
	s_mov_b32 s1, 0x8000
	s_cmp_eq_u32 s0, 64
	global_load_dwordx4 v[80:83], v[4:5], off
	s_nop 0
	global_load_dwordx4 v[4:7], v[2:3], off
	global_load_dwordx4 v[8:11], v[2:3], off offset:64
	v_add_co_u32_e32 v2, vcc, s1, v2
	s_cselect_b32 s1, 0, 0x20000
	v_add_u32_e32 v0, s1, v186
	v_addc_co_u32_e32 v3, vcc, 0, v3, vcc
	v_add_u32_e32 v20, 0x8000, v0
	v_mov_b32_e32 v21, v1
	global_load_dwordx4 v[12:15], v[2:3], off
	global_load_dwordx4 v[16:19], v[2:3], off offset:64
	v_lshl_add_u64 v[2:3], v[0:1], 1, s[78:79]
	v_lshl_add_u64 v[24:25], v[20:21], 1, s[78:79]
	s_barrier
	global_load_dwordx4 v[20:23], v[2:3], off
	s_nop 0
	global_load_dwordx4 v[24:27], v[24:25], off
	v_add_u32_e32 v2, 0x10000, v0
	v_add_u32_e32 v0, 0x18000, v0
	s_cselect_b32 s1, 0, 0x80
	v_mov_b32_e32 v3, v1
	v_lshl_add_u64 v[32:33], v[0:1], 1, s[78:79]
	v_add_u32_e32 v0, s1, v188
	v_lshl_add_u64 v[2:3], v[2:3], 1, s[78:79]
	v_add_u32_e32 v36, 0x41000, v0
	v_mov_b32_e32 v37, v1
	global_load_dwordx4 v[28:31], v[2:3], off
	s_nop 0
	global_load_dwordx4 v[32:35], v[32:33], off
	v_lshl_add_u64 v[2:3], v[0:1], 1, s[70:71]
	v_lshl_add_u64 v[40:41], v[36:37], 1, s[70:71]
	global_load_dwordx4 v[36:39], v[2:3], off
	s_nop 0
	global_load_dwordx4 v[40:43], v[40:41], off
	v_add_u32_e32 v2, 0x82000, v0
	v_mov_b32_e32 v3, v1
	v_add_u32_e32 v0, 0xc3000, v0
	v_lshl_add_u64 v[2:3], v[2:3], 1, s[70:71]
	v_lshl_add_u64 v[48:49], v[0:1], 1, s[70:71]
	global_load_dwordx4 v[44:47], v[2:3], off
	s_nop 0
	global_load_dwordx4 v[48:51], v[48:49], off
	s_movk_i32 s1, 0x110
	v_mul_lo_u32 v84, v84, s1
	v_lshlrev_b32_e32 v85, 1, v85
	v_add3_u32 v230, 0, v84, v85
	v_and_b32_e32 v0, 15, v181
	v_bfe_u32 v2, v181, 4, 4
	v_not_b32_e32 v3, v2
	v_and_b32_e32 v3, 1, v3
	v_lshlrev_b32_e32 v3, 1, v3
	v_add_u32_e32 v2, 4, v2
	v_bfe_u32 v2, v2, 3, 1
	v_or_b32_e32 v3, v3, v2
	v_xor_b32_e32 v3, v3, v0
	v_sub_u32_e32 v3, v3, v0
	v_lshl_add_u32 v230, v3, 4, v230
	s_waitcnt vmcnt(19)
	ds_write_b128 v230, v[52:55]
	s_waitcnt vmcnt(18)
	ds_write_b128 v230, v[56:59] offset:8704
	s_waitcnt vmcnt(17)
	ds_write_b128 v230, v[60:63] offset:17408
	s_waitcnt vmcnt(16)
	ds_write_b128 v230, v[64:67] offset:26112
	s_mov_b32 s98, 0x11000
	v_and_b32_e32 v0, 15, v181
	v_bfe_u32 v2, v181, 4, 4
	v_not_b32_e32 v54, v2
	v_and_b32_e32 v54, 1, v54
	v_lshlrev_b32_e32 v54, 1, v54
	v_add_u32_e32 v55, 4, v2
	v_bfe_u32 v55, v55, 3, 1
	v_or_b32_e32 v54, v54, v55
	v_xor_b32_e32 v3, v0, v54
	v_lshlrev_b32_e32 v3, 4, v3
	v_sub_u32_e32 v3, v230, v3
	v_add_u32_e32 v3, s98, v3
	v_lshrrev_b32_e32 v55, 2, v0
	v_lshl_add_u32 v3, v55, 6, v3
	v_bfe_u32 v55, v0, 1, 1
	v_lshl_add_u32 v3, v55, 3, v3
	v_and_b32_e32 v55, 1, v0
	v_lshlrev_b32_e32 v55, 1, v55
	v_xor_b32_e32 v55, v55, v54
	v_xor_b32_e32 v54, 1, v55
	v_lshl_add_u32 v52, v55, 4, v3
	v_lshl_add_u32 v53, v54, 4, v3
	v_bfe_u32 v2, v224, 4, 2
	v_not_b32_e32 v3, v222
	v_and_b32_e32 v3, 1, v3
	v_lshlrev_b32_e32 v3, 1, v3
	v_add_u32_e32 v55, 4, v222
	v_bfe_u32 v55, v55, 3, 1
	v_or_b32_e32 v3, v3, v55
	v_xor_b32_e32 v3, v3, v2
	v_lshlrev_b32_e32 v3, 4, v3
	v_readlane_b32 s1, v255, 8
	s_waitcnt vmcnt(15)
	ds_write_b64 v52, v[68:69]
	ds_write_b64 v53, v[70:71]
	s_waitcnt vmcnt(14)
	ds_write_b64 v52, v[72:73] offset:8704
	ds_write_b64 v53, v[74:75] offset:8704
	s_waitcnt vmcnt(13)
	ds_write_b64 v52, v[76:77] offset:17408
	ds_write_b64 v53, v[78:79] offset:17408
	v_and_b32_e32 v0, 63, v224
	v_lshlrev_b32_e32 v54, 7, v225
	v_lshlrev_b32_e32 v183, 2, v2
	s_waitcnt vmcnt(12)
; #define MFMA(a, b, c) __builtin_amdgcn_mfma_f32_16x16x32_bf16(a, b, c, 0, 0, 0)
; DEV float shfl_l(float v, int srclane) { return __int_as_float(__builtin_amdgcn_ds_bpermute(srclane << 2, __float_as_int(v))); }
; DEV void attn_item(const Params& p, int layer, int h, int qb, float lam, bf16_t* lds) {
;     ...
;   f32x4 o[2][8];
; #pragma unroll
;   for (int i = 0; i < 2; i++)
; #pragma unroll
;     for (int j = 0; j < 8; j++) o[i][j] = (f32x4){0.f, 0.f, 0.f, 0.f};
;   float mrun0 = -1e30f, mrun1 = -1e30f, lrun0 = 0.f, lrun1 = 0.f;
;   u32x4 rk0, rk1, rk2, rk3, rv0, rv1, rv2, rv3;
;   const unsigned ko = (unsigned)(lrow * 1024 + h * 128 + lc8);
;   const unsigned vo = (unsigned)((h * 128 + lrow) * LT + lc8);
;     ...
; #pragma unroll
;       for (int j = 0; j < 8; j++)
; #pragma unroll
;         for (int r = 0; r < 4; r++) { const float pv = ex2(s[i][j][r] - mnew); s[i][j][r] = pv; ps += pv; }
;       if (i == 0) { mrun0 = mnew; lrun0 = lrun0 * al[0] + ps; } else { mrun1 = mnew; lrun1 = lrun1 * al[1] + ps; }
;     }
;     if (__builtin_amdgcn_ballot_w64(al[0] != 1.f || al[1] != 1.f) != 0ull) {
; #pragma unroll
;       for (int i = 0; i < 2; i++) {
;         float ao[4];
; #pragma unroll
;         for (int r = 0; r < 4; r++) ao[r] = shfl_l(al[i], lg * 4 + r);
; #pragma unroll
;         for (int je = 0; je < 8; je++)
; #pragma unroll
;           for (int r = 0; r < 4; r++) o[i][je][r] *= ao[r];
;       }
;     }
; #pragma unroll
;     for (int ks = 0; ks < 4; ks++) {
;       union { u32x4 u; bf16x8 v; } pf0, pf1;
;       pf0.u[0] = pack2(s[0][2 * ks][0], s[0][2 * ks][1]);
;       pf0.u[1] = pack2(s[0][2 * ks][2], s[0][2 * ks][3]);
;       pf0.u[2] = pack2(s[0][2 * ks + 1][0], s[0][2 * ks + 1][1]);
;       pf0.u[3] = pack2(s[0][2 * ks + 1][2], s[0][2 * ks + 1][3]);
;       pf1.u[0] = pack2(s[1][2 * ks][0], s[1][2 * ks][1]);
;       pf1.u[1] = pack2(s[1][2 * ks][2], s[1][2 * ks][3]);
;       pf1.u[2] = pack2(s[1][2 * ks + 1][0], s[1][2 * ks + 1][1]);
;       pf1.u[3] = pack2(s[1][2 * ks + 1][2], s[1][2 * ks + 1][3]);
; #pragma unroll
;       for (int je = 0; je < 8; je++) {
;         const bf16_t* vp = vq + je * 16 * PS + ks * 32;
;         union { uint2 u[2]; bf16x8 v; } vf;
;         vf.u[0] = *(const uint2*)vp;
;         vf.u[1] = *(const uint2*)(vp + 16);
;         o[0][je] = MFMA(pf0.v, vf.v, o[0][je]);
;         o[1][je] = MFMA(pf1.v, vf.v, o[1][je]);
;       }
	ds_write_b64 v52, v[80:81] offset:26112
	ds_write_b64 v53, v[82:83] offset:26112
	v_mul_u32_u24_e32 v52, 0x88, v222
	v_lshlrev_b32_e32 v52, 1, v52
	v_add_u32_e32 v53, 0, v52
	v_add3_u32 v232, s1, v52, v3
	v_add3_u32 v231, v53, v54, v3
	v_mov_b32_e32 v2, v1
	v_mov_b32_e32 v3, v1
	v_lshlrev_b32_e32 v185, 2, v0
	v_mov_b32_e32 v0, v1
	v_mov_b32_e32 v192, 0xf149f2ca
	v_mov_b32_e32 v190, 0
	v_mov_b64_e32 v[58:59], v[2:3]
	v_mov_b64_e32 v[62:63], v[2:3]
	v_mov_b64_e32 v[66:67], v[2:3]
	v_mov_b64_e32 v[70:71], v[2:3]
	v_mov_b64_e32 v[74:75], v[2:3]
	v_mov_b64_e32 v[78:79], v[2:3]
	v_mov_b64_e32 v[82:83], v[2:3]
	v_mov_b64_e32 v[86:87], v[2:3]
	v_mov_b64_e32 v[106:107], v[2:3]
	v_mov_b64_e32 v[90:91], v[2:3]
	v_mov_b64_e32 v[110:111], v[2:3]
	v_mov_b64_e32 v[94:95], v[2:3]
	v_mov_b64_e32 v[114:115], v[2:3]
	v_mov_b64_e32 v[98:99], v[2:3]
	v_mov_b64_e32 v[102:103], v[2:3]
	v_mov_b64_e32 v[54:55], v[2:3]
	v_mov_b32_e32 v217, 0x3e38aa3b
	v_mov_b32_e32 v180, 0x42000000
	s_mov_b32 s77, 0
	v_xor_b32_e32 v229, 64, v185
	v_xor_b32_e32 v228, 0x80, v185
	v_or_b32_e32 v233, 16, v184
	v_or_b32_e32 v227, 4, v182
	v_or_b32_e32 v189, 8, v182
	v_or_b32_e32 v187, 12, v182
	s_sub_i32 s82, 0x41, s0
	v_mov_b32_e32 v234, v183
	v_mov_b64_e32 v[56:57], v[0:1]
	v_mov_b64_e32 v[60:61], v[0:1]
	v_mov_b64_e32 v[64:65], v[0:1]
	v_mov_b64_e32 v[68:69], v[0:1]
	v_mov_b64_e32 v[72:73], v[0:1]
	v_mov_b64_e32 v[76:77], v[0:1]
	v_mov_b64_e32 v[80:81], v[0:1]
	v_mov_b64_e32 v[84:85], v[0:1]
	v_mov_b64_e32 v[104:105], v[0:1]
	v_mov_b64_e32 v[88:89], v[0:1]
	v_mov_b64_e32 v[108:109], v[0:1]
	v_mov_b64_e32 v[92:93], v[0:1]
	v_mov_b64_e32 v[112:113], v[0:1]
	v_mov_b64_e32 v[96:97], v[0:1]
	v_mov_b64_e32 v[100:101], v[0:1]
	v_mov_b64_e32 v[52:53], v[0:1]
	v_mov_b32_e32 v191, v190
	v_mov_b32_e32 v193, v192
	s_waitcnt lgkmcnt(0)
	s_barrier
	s_branch .LBB0_708
.LBB0_707:
	v_sub_f32_e32 v0, v176, v193
	v_exp_f32_e32 v199, v0
	v_sub_f32_e32 v0, v177, v193
	v_exp_f32_e32 v203, v0
	v_sub_f32_e32 v0, v178, v193
	v_exp_f32_e32 v195, v0
	v_sub_f32_e32 v0, v179, v193
	v_exp_f32_e32 v197, v0
	v_sub_f32_e32 v0, v172, v193
	v_exp_f32_e32 v201, v0
	v_sub_f32_e32 v0, v173, v193
	v_exp_f32_e32 v177, v0
	v_sub_f32_e32 v0, v174, v193
	v_exp_f32_e32 v179, v0
	v_sub_f32_e32 v0, v175, v193
	v_exp_f32_e32 v173, v0
	v_sub_f32_e32 v0, v160, v193
	v_exp_f32_e32 v175, v0
	v_sub_f32_e32 v0, v161, v193
	v_exp_f32_e32 v161, v0
	v_sub_f32_e32 v0, v168, v192
	v_exp_f32_e32 v198, v0
	v_sub_f32_e32 v0, v169, v192
	v_exp_f32_e32 v202, v0
	v_sub_f32_e32 v0, v170, v192
	v_exp_f32_e32 v194, v0
	v_sub_f32_e32 v0, v171, v192
	v_exp_f32_e32 v196, v0
	v_sub_f32_e32 v0, v164, v192
	v_exp_f32_e32 v200, v0
	v_sub_f32_e32 v0, v165, v192
	v_exp_f32_e32 v176, v0
	v_sub_f32_e32 v0, v166, v192
	v_exp_f32_e32 v178, v0
	v_sub_f32_e32 v0, v167, v192
	v_exp_f32_e32 v172, v0
	v_lshl_add_u32 v0, s67, 1, v232
	v_cvt_pk_bf16_f32 v236, v199, v203
	v_cvt_pk_bf16_f32 v237, v195, v197
	v_cvt_pk_bf16_f32 v238, v201, v177
	v_cvt_pk_bf16_f32 v239, v179, v173
	ds_read_b128 v[164:167], v0
	v_cvt_pk_bf16_f32 v240, v198, v202
	v_cvt_pk_bf16_f32 v241, v194, v196
	v_cvt_pk_bf16_f32 v242, v200, v176
	v_cvt_pk_bf16_f32 v243, v178, v172
	v_add_u32_e32 v204, 0x2000, v0
	v_add_u32_e32 v205, 0x3000, v0
	ds_read_b128 v[244:247], v204 offset:512
	ds_read_b128 v[248:251], v205 offset:768
	v_sub_f32_e32 v160, v162, v193
	v_sub_f32_e32 v152, v152, v192
	s_waitcnt lgkmcnt(2)
	v_mfma_f32_16x16x32_bf16 v[100:103], v[236:239], v[164:167], v[100:103]
	v_exp_f32_e32 v174, v152
	v_sub_f32_e32 v152, v153, v192
	v_add_u32_e32 v206, 0x1000, v0
	v_mfma_f32_16x16x32_bf16 v[80:83], v[240:243], v[164:167], v[80:83]
	v_exp_f32_e32 v165, v160
	v_sub_f32_e32 v160, v163, v193
	v_exp_f32_e32 v163, v160
	v_add_u32_e32 v235, 0x4000, v0
	v_exp_f32_e32 v160, v152
	v_sub_f32_e32 v152, v154, v192
	v_add_u32_e32 v212, 0x5000, v0
	ds_read_b128 v[168:171], v206 offset:256
	s_waitcnt lgkmcnt(2)
	v_mfma_f32_16x16x32_bf16 v[112:115], v[236:239], v[244:247], v[112:115]
	v_exp_f32_e32 v164, v152
	v_sub_f32_e32 v152, v155, v192
	v_add_u32_e32 v252, 0x6000, v0
	v_mfma_f32_16x16x32_bf16 v[72:75], v[240:243], v[244:247], v[72:75]
	ds_read_b128 v[244:247], v235 offset:1024
	v_exp_f32_e32 v162, v152
	ds_read_b128 v[152:155], v252 offset:1536
	s_waitcnt lgkmcnt(3)
	v_mfma_f32_16x16x32_bf16 v[92:95], v[236:239], v[248:251], v[92:95]
	v_sub_f32_e32 v156, v156, v193
	v_exp_f32_e32 v167, v156
	v_sub_f32_e32 v156, v157, v193
	v_mfma_f32_16x16x32_bf16 v[68:71], v[240:243], v[248:251], v[68:71]
	ds_read_b128 v[248:251], v212 offset:1280
	v_exp_f32_e32 v157, v156
	v_sub_f32_e32 v156, v158, v193
	s_waitcnt lgkmcnt(3)
	v_mfma_f32_16x16x32_bf16 v[96:99], v[236:239], v[168:171], v[96:99]
	v_sub_f32_e32 v148, v148, v192
	v_add_u32_e32 v216, 0x7000, v0
	v_exp_f32_e32 v166, v148
	v_mfma_f32_16x16x32_bf16 v[76:79], v[240:243], v[168:171], v[76:79]
	v_exp_f32_e32 v169, v156
	v_sub_f32_e32 v156, v159, v193
	v_exp_f32_e32 v159, v156
	s_waitcnt lgkmcnt(2)
	v_mfma_f32_16x16x32_bf16 v[108:111], v[236:239], v[244:247], v[108:111]
	v_sub_f32_e32 v148, v150, v192
	v_exp_f32_e32 v168, v148
	ds_read_b128 v[208:211], v235 offset:1088
	v_mfma_f32_16x16x32_bf16 v[64:67], v[240:243], v[244:247], v[64:67]
	v_sub_f32_e32 v128, v128, v193
	v_exp_f32_e32 v171, v128
	v_sub_f32_e32 v128, v129, v193
	s_waitcnt lgkmcnt(1)
; #define MFMA(a, b, c) __builtin_amdgcn_mfma_f32_16x16x32_bf16(a, b, c, 0, 0, 0)
; DEV float shfl_l(float v, int srclane) { return __int_as_float(__builtin_amdgcn_ds_bpermute(srclane << 2, __float_as_int(v))); }
; DEV float ex2(float x) { return __builtin_amdgcn_exp2f(x); }
; DEV void attn_item(const Params& p, int layer, int h, int qb, float lam, bf16_t* lds) {
;     ...
; #pragma unroll
;       for (int j = 0; j < 8; j++)
; #pragma unroll
;         for (int r = 0; r < 4; r++) { const float pv = ex2(s[i][j][r] - mnew); s[i][j][r] = pv; ps += pv; }
;       if (i == 0) { mrun0 = mnew; lrun0 = lrun0 * al[0] + ps; } else { mrun1 = mnew; lrun1 = lrun1 * al[1] + ps; }
;     }
;     if (__builtin_amdgcn_ballot_w64(al[0] != 1.f || al[1] != 1.f) != 0ull) {
; #pragma unroll
;       for (int i = 0; i < 2; i++) {
;         float ao[4];
; #pragma unroll
;         for (int r = 0; r < 4; r++) ao[r] = shfl_l(al[i], lg * 4 + r);
; #pragma unroll
;         for (int je = 0; je < 8; je++)
; #pragma unroll
;           for (int r = 0; r < 4; r++) o[i][je][r] *= ao[r];
;       }
;     }
; #pragma unroll
;     for (int ks = 0; ks < 4; ks++) {
;       union { u32x4 u; bf16x8 v; } pf0, pf1;
;       pf0.u[0] = pack2(s[0][2 * ks][0], s[0][2 * ks][1]);
;       pf0.u[1] = pack2(s[0][2 * ks][2], s[0][2 * ks][3]);
;       pf0.u[2] = pack2(s[0][2 * ks + 1][0], s[0][2 * ks + 1][1]);
;       pf0.u[3] = pack2(s[0][2 * ks + 1][2], s[0][2 * ks + 1][3]);
;       pf1.u[0] = pack2(s[1][2 * ks][0], s[1][2 * ks][1]);
;       pf1.u[1] = pack2(s[1][2 * ks][2], s[1][2 * ks][3]);
;       pf1.u[2] = pack2(s[1][2 * ks + 1][0], s[1][2 * ks + 1][1]);
;       pf1.u[3] = pack2(s[1][2 * ks + 1][2], s[1][2 * ks + 1][3]);
; #pragma unroll
;       for (int je = 0; je < 8; je++) {
;         const bf16_t* vp = vq + je * 16 * PS + ks * 32;
;         union { uint2 u[2]; bf16x8 v; } vf;
;         vf.u[0] = *(const uint2*)vp;
;         vf.u[1] = *(const uint2*)(vp + 16);
;         o[0][je] = MFMA(pf0.v, vf.v, o[0][je]);
;         o[1][je] = MFMA(pf1.v, vf.v, o[1][je]);
;       }
;     }
	v_mfma_f32_16x16x32_bf16 v[244:247], v[240:243], v[248:251], v[60:63]
	v_exp_f32_e32 v221, v128
	v_sub_f32_e32 v128, v130, v193
	v_sub_f32_e32 v124, v124, v193
	v_sub_f32_e32 v60, v149, v192
	v_exp_f32_e32 v156, v60
	v_mfma_f32_16x16x32_bf16 v[104:107], v[236:239], v[152:155], v[104:107]
	ds_read_b128 v[60:63], v216 offset:1792
	v_sub_f32_e32 v120, v120, v192
	v_exp_f32_e32 v170, v120
	v_mfma_f32_16x16x32_bf16 v[152:155], v[240:243], v[152:155], v[56:59]
	v_sub_f32_e32 v120, v121, v192
	v_sub_f32_e32 v116, v116, v192
	v_exp_f32_e32 v220, v120
	v_sub_f32_e32 v56, v151, v192
	v_exp_f32_e32 v158, v56
	v_mfma_f32_16x16x32_bf16 v[88:91], v[236:239], v[248:251], v[88:91]
	ds_read_b128 v[56:59], v0 offset:64
	v_cvt_pk_bf16_f32 v248, v174, v160
	v_cvt_pk_bf16_f32 v249, v164, v162
	s_waitcnt lgkmcnt(1)
	v_mfma_f32_16x16x32_bf16 v[148:151], v[236:239], v[60:63], v[84:87]
	v_cvt_pk_bf16_f32 v236, v175, v161
	v_cvt_pk_bf16_f32 v237, v165, v163
	v_cvt_pk_bf16_f32 v238, v167, v157
	v_cvt_pk_bf16_f32 v239, v169, v159
	v_cvt_pk_bf16_f32 v250, v166, v156
	v_cvt_pk_bf16_f32 v251, v168, v158
	s_waitcnt lgkmcnt(0)
	v_mfma_f32_16x16x32_bf16 v[100:103], v[236:239], v[56:59], v[100:103]
	ds_read_b128 v[84:87], v204 offset:576
	v_sub_f32_e32 v120, v122, v192
	v_mfma_f32_16x16x32_bf16 v[80:83], v[248:251], v[56:59], v[80:83]
	ds_read_b128 v[56:59], v206 offset:320
	v_mfma_f32_16x16x32_bf16 v[240:243], v[240:243], v[60:63], v[52:55]
	v_sub_f32_e32 v60, v133, v192
	v_exp_f32_e32 v60, v60
	s_nop 0
	v_sub_f32_e32 v52, v144, v193
	v_exp_f32_e32 v53, v52
	v_sub_f32_e32 v52, v145, v193
	v_exp_f32_e32 v55, v52
	v_sub_f32_e32 v52, v146, v193
	s_waitcnt lgkmcnt(0)
	v_mfma_f32_16x16x32_bf16 v[96:99], v[236:239], v[56:59], v[96:99]
	v_sub_f32_e32 v54, v137, v192
	v_exp_f32_e32 v54, v54
	v_mfma_f32_16x16x32_bf16 v[76:79], v[248:251], v[56:59], v[76:79]
	v_exp_f32_e32 v57, v52
	v_sub_f32_e32 v52, v147, v193
	ds_read_b128 v[144:147], v205 offset:832
	v_exp_f32_e32 v63, v52
	v_sub_f32_e32 v52, v140, v193
	v_exp_f32_e32 v59, v52
	v_sub_f32_e32 v52, v141, v193
	v_exp_f32_e32 v61, v52
	v_sub_f32_e32 v52, v142, v193
	v_mfma_f32_16x16x32_bf16 v[112:115], v[236:239], v[84:87], v[112:115]
	v_sub_f32_e32 v58, v139, v192
	v_sub_f32_e32 v56, v138, v192
	v_exp_f32_e32 v62, v58
	v_mfma_f32_16x16x32_bf16 v[72:75], v[248:251], v[84:87], v[72:75]
	v_exp_f32_e32 v85, v52
	v_sub_f32_e32 v52, v143, v193
	v_exp_f32_e32 v87, v52
	s_waitcnt lgkmcnt(0)
	v_mfma_f32_16x16x32_bf16 v[92:95], v[236:239], v[144:147], v[92:95]
	v_sub_f32_e32 v52, v136, v192
	ds_read_b128 v[140:143], v212 offset:1344
	ds_read_b128 v[136:139], v252 offset:1600
	v_mfma_f32_16x16x32_bf16 v[68:71], v[248:251], v[144:147], v[68:71]
	v_sub_f32_e32 v58, v132, v192
	v_sub_f32_e32 v84, v134, v192
	ds_read_b128 v[144:147], v216 offset:1856
	v_sub_f32_e32 v86, v135, v192
	v_exp_f32_e32 v52, v52
	v_exp_f32_e32 v56, v56
	v_exp_f32_e32 v58, v58
	v_exp_f32_e32 v84, v84
	v_exp_f32_e32 v86, v86
	v_mfma_f32_16x16x32_bf16 v[108:111], v[236:239], v[208:211], v[108:111]
	v_mfma_f32_16x16x32_bf16 v[64:67], v[248:251], v[208:211], v[64:67]
	v_cvt_pk_bf16_f32 v208, v52, v54
	v_cvt_pk_bf16_f32 v209, v56, v62
	v_cvt_pk_bf16_f32 v210, v58, v60
	s_waitcnt lgkmcnt(2)
	v_mfma_f32_16x16x32_bf16 v[88:91], v[236:239], v[140:143], v[88:91]
	v_cvt_pk_bf16_f32 v211, v84, v86
	s_waitcnt lgkmcnt(1)
	v_mfma_f32_16x16x32_bf16 v[104:107], v[236:239], v[136:139], v[104:107]
	s_waitcnt lgkmcnt(0)
	v_mfma_f32_16x16x32_bf16 v[132:135], v[236:239], v[144:147], v[148:151]
	ds_read_b128 v[236:239], v204 offset:640
	s_nop 1
	v_cvt_pk_bf16_f32 v148, v53, v55
	v_cvt_pk_bf16_f32 v149, v57, v63
	v_cvt_pk_bf16_f32 v150, v59, v61
	v_cvt_pk_bf16_f32 v151, v85, v87
	v_mfma_f32_16x16x32_bf16 v[144:147], v[248:251], v[144:147], v[240:243]
	s_nop 2
	v_exp_f32_e32 v241, v128
	v_sub_f32_e32 v128, v131, v193
	v_exp_f32_e32 v243, v128
	ds_read_b128 v[128:131], v205 offset:896
	s_waitcnt lgkmcnt(1)
	v_mfma_f32_16x16x32_bf16 v[112:115], v[148:151], v[236:239], v[112:115]
	v_exp_f32_e32 v240, v120
	v_sub_f32_e32 v120, v123, v192
	v_exp_f32_e32 v242, v120
	v_mfma_f32_16x16x32_bf16 v[72:75], v[208:211], v[236:239], v[72:75]
	v_exp_f32_e32 v237, v124
	v_sub_f32_e32 v124, v125, v193
	v_exp_f32_e32 v239, v124
	v_sub_f32_e32 v124, v126, v193
	v_exp_f32_e32 v236, v116
	v_sub_f32_e32 v116, v117, v192
	v_mfma_f32_16x16x32_bf16 v[140:143], v[248:251], v[140:143], v[244:247]
	v_exp_f32_e32 v238, v116
	v_sub_f32_e32 v116, v118, v192
	ds_read_b128 v[120:123], v252 offset:1664
	v_mfma_f32_16x16x32_bf16 v[136:139], v[248:251], v[136:139], v[152:155]
	v_exp_f32_e32 v245, v124
	v_sub_f32_e32 v124, v127, v193
	v_exp_f32_e32 v247, v124
	ds_read_b128 v[152:155], v0 offset:128
	s_waitcnt lgkmcnt(2)
	v_mfma_f32_16x16x32_bf16 v[92:95], v[148:151], v[128:131], v[92:95]
	ds_read_b128 v[124:127], v212 offset:1408
	v_exp_f32_e32 v244, v116
	v_sub_f32_e32 v116, v119, v192
	v_mfma_f32_16x16x32_bf16 v[68:71], v[208:211], v[128:131], v[68:71]
	ds_read_b128 v[128:131], v216 offset:1920
	v_exp_f32_e32 v246, v116
	s_waitcnt lgkmcnt(2)
	v_mfma_f32_16x16x32_bf16 v[100:103], v[148:151], v[152:155], v[100:103]
	v_mfma_f32_16x16x32_bf16 v[80:83], v[208:211], v[152:155], v[80:83]
	ds_read_b128 v[152:155], v206 offset:384
	s_waitcnt lgkmcnt(2)
	v_mfma_f32_16x16x32_bf16 v[88:91], v[148:151], v[124:127], v[88:91]
	v_mfma_f32_16x16x32_bf16 v[124:127], v[208:211], v[124:127], v[140:143]
	v_mfma_f32_16x16x32_bf16 v[104:107], v[148:151], v[120:123], v[104:107]
	s_nop 1
	v_cvt_pk_bf16_f32 v140, v170, v220
	v_cvt_pk_bf16_f32 v141, v240, v242
	v_cvt_pk_bf16_f32 v142, v236, v238
	v_mfma_f32_16x16x32_bf16 v[120:123], v[208:211], v[120:123], v[136:139]
	v_cvt_pk_bf16_f32 v143, v244, v246
	s_waitcnt lgkmcnt(1)
; #define MFMA(a, b, c) __builtin_amdgcn_mfma_f32_16x16x32_bf16(a, b, c, 0, 0, 0)
; DEV float shfl_l(float v, int srclane) { return __int_as_float(__builtin_amdgcn_ds_bpermute(srclane << 2, __float_as_int(v))); }
; DEV void attn_item(const Params& p, int layer, int h, int qb, float lam, bf16_t* lds) {
;     ...
;   for (int kb = 0; kb <= qb; kb++) {
;     const int cur = kb & 1;
;     const bf16_t* kp = KV + cur * TS + lr * PS + grp * 64 + lg * 8;
;     const bf16_t* vq = KV + 2 * TS + cur * TS + lr * PS + lg * 4;
;     {
;       bf16_t* sp = KV + (cur ^ 1) * TS + lrow * PS + lc8;
;       ASTORE(sp)
;     }
;     ...
; #pragma unroll
;       for (int j = 0; j < 8; j++)
; #pragma unroll
;         for (int r = 0; r < 4; r++) { const float pv = ex2(s[i][j][r] - mnew); s[i][j][r] = pv; ps += pv; }
;       if (i == 0) { mrun0 = mnew; lrun0 = lrun0 * al[0] + ps; } else { mrun1 = mnew; lrun1 = lrun1 * al[1] + ps; }
;     }
;     if (__builtin_amdgcn_ballot_w64(al[0] != 1.f || al[1] != 1.f) != 0ull) {
; #pragma unroll
;       for (int i = 0; i < 2; i++) {
;         float ao[4];
; #pragma unroll
;         for (int r = 0; r < 4; r++) ao[r] = shfl_l(al[i], lg * 4 + r);
; #pragma unroll
;         for (int je = 0; je < 8; je++)
; #pragma unroll
;           for (int r = 0; r < 4; r++) o[i][je][r] *= ao[r];
;       }
;     }
; #pragma unroll
;     for (int ks = 0; ks < 4; ks++) {
;       union { u32x4 u; bf16x8 v; } pf0, pf1;
;       pf0.u[0] = pack2(s[0][2 * ks][0], s[0][2 * ks][1]);
;       pf0.u[1] = pack2(s[0][2 * ks][2], s[0][2 * ks][3]);
;       pf0.u[2] = pack2(s[0][2 * ks + 1][0], s[0][2 * ks + 1][1]);
;       pf0.u[3] = pack2(s[0][2 * ks + 1][2], s[0][2 * ks + 1][3]);
;       pf1.u[0] = pack2(s[1][2 * ks][0], s[1][2 * ks][1]);
;       pf1.u[1] = pack2(s[1][2 * ks][2], s[1][2 * ks][3]);
;       pf1.u[2] = pack2(s[1][2 * ks + 1][0], s[1][2 * ks + 1][1]);
;       pf1.u[3] = pack2(s[1][2 * ks + 1][2], s[1][2 * ks + 1][3]);
; #pragma unroll
;       for (int je = 0; je < 8; je++) {
;         const bf16_t* vp = vq + je * 16 * PS + ks * 32;
;         union { uint2 u[2]; bf16x8 v; } vf;
;         vf.u[0] = *(const uint2*)vp;
;         vf.u[1] = *(const uint2*)(vp + 16);
;         o[0][je] = MFMA(pf0.v, vf.v, o[0][je]);
;         o[1][je] = MFMA(pf1.v, vf.v, o[1][je]);
;       }
;     }
;     __builtin_amdgcn_sched_barrier(0);
;     __syncthreads();
;   }
	v_mfma_f32_16x16x32_bf16 v[116:119], v[148:151], v[128:131], v[132:135]
	ds_read_b128 v[136:139], v0 offset:192
	s_nop 1
	v_cvt_pk_bf16_f32 v132, v171, v221
	v_cvt_pk_bf16_f32 v133, v241, v243
	v_cvt_pk_bf16_f32 v134, v237, v239
	v_cvt_pk_bf16_f32 v135, v245, v247
	s_waitcnt lgkmcnt(1)
	v_mfma_f32_16x16x32_bf16 v[96:99], v[148:151], v[152:155], v[96:99]
	v_mfma_f32_16x16x32_bf16 v[76:79], v[208:211], v[152:155], v[76:79]
	ds_read_b128 v[152:155], v235 offset:1152
	s_waitcnt lgkmcnt(1)
	v_mfma_f32_16x16x32_bf16 v[100:103], v[132:135], v[136:139], v[100:103]
	v_mfma_f32_16x16x32_bf16 v[80:83], v[140:143], v[136:139], v[80:83]
	ds_read_b128 v[136:139], v206 offset:448
	v_mfma_f32_16x16x32_bf16 v[128:131], v[208:211], v[128:131], v[144:147]
	s_nop 2
	v_add_f32_e64 v144, v198, 0
	v_add_f32_e64 v145, v199, 0
	s_waitcnt lgkmcnt(1)
	v_mfma_f32_16x16x32_bf16 v[108:111], v[148:151], v[152:155], v[108:111]
	v_add_f32_e64 v148, v202, v144
	v_add_f32_e64 v149, v203, v145
	ds_read_b128 v[144:147], v204 offset:704
	s_waitcnt lgkmcnt(1)
	v_mfma_f32_16x16x32_bf16 v[96:99], v[132:135], v[136:139], v[96:99]
	v_mfma_f32_16x16x32_bf16 v[76:79], v[140:143], v[136:139], v[76:79]
	v_add_f32_e64 v136, v194, v148
	v_add_f32_e64 v137, v195, v149
	v_pk_add_f32 v[136:137], v[196:197], v[136:137]
	s_waitcnt lgkmcnt(0)
	v_mfma_f32_16x16x32_bf16 v[112:115], v[132:135], v[144:147], v[112:115]
	v_add_f32_e64 v136, v200, v136
	v_add_f32_e64 v137, v201, v137
	v_pk_add_f32 v[136:137], v[176:177], v[136:137]
	v_mfma_f32_16x16x32_bf16 v[72:75], v[140:143], v[144:147], v[72:75]
	v_add_f32_e64 v148, v178, v136
	v_add_f32_e64 v149, v179, v137
	ds_read_b128 v[136:139], v205 offset:960
	v_pk_add_f32 v[144:145], v[172:173], v[148:149]
	s_waitcnt lgkmcnt(0)
	v_mfma_f32_16x16x32_bf16 v[92:95], v[132:135], v[136:139], v[92:95]
	v_add_f32_e64 v144, v174, v144
	v_add_f32_e64 v145, v175, v145
	v_pk_add_f32 v[144:145], v[160:161], v[144:145]
	v_mfma_f32_16x16x32_bf16 v[68:71], v[140:143], v[136:139], v[68:71]
	v_add_f32_e64 v144, v164, v144
	v_add_f32_e64 v145, v165, v145
	v_pk_add_f32 v[148:149], v[162:163], v[144:145]
	ds_read_b128 v[144:147], v235 offset:1216
	v_pk_add_f32 v[136:137], v[166:167], v[148:149]
	v_mfma_f32_16x16x32_bf16 v[64:67], v[208:211], v[152:155], v[64:67]
	v_add_f32_e64 v136, v156, v136
	v_add_f32_e64 v137, v157, v137
	v_pk_add_f32 v[136:137], v[168:169], v[136:137]
	s_waitcnt lgkmcnt(0)
	v_mfma_f32_16x16x32_bf16 v[108:111], v[132:135], v[144:147], v[108:111]
	v_add_f32_e64 v136, v158, v136
	v_add_f32_e64 v137, v159, v137
	v_pk_add_f32 v[52:53], v[52:53], v[136:137]
	ds_read_b128 v[136:139], v212 offset:1472
	v_pk_add_f32 v[52:53], v[54:55], v[52:53]
	v_mfma_f32_16x16x32_bf16 v[64:67], v[140:143], v[144:147], v[64:67]
	v_add_f32_e64 v52, v56, v52
	v_add_f32_e64 v53, v57, v53
	v_pk_add_f32 v[52:53], v[62:63], v[52:53]
	s_waitcnt lgkmcnt(0)
	v_mfma_f32_16x16x32_bf16 v[88:91], v[132:135], v[136:139], v[88:91]
	v_add_f32_e64 v52, v58, v52
	v_add_f32_e64 v53, v59, v53
	v_pk_add_f32 v[56:57], v[60:61], v[52:53]
	ds_read_b128 v[52:55], v252 offset:1728
	v_pk_add_f32 v[56:57], v[84:85], v[56:57]
	v_mfma_f32_16x16x32_bf16 v[60:63], v[140:143], v[136:139], v[124:127]
	v_add_f32_e64 v56, v86, v56
	v_add_f32_e64 v57, v87, v57
	v_pk_add_f32 v[56:57], v[170:171], v[56:57]
	s_waitcnt lgkmcnt(0)
	v_mfma_f32_16x16x32_bf16 v[104:107], v[132:135], v[52:55], v[104:107]
	v_add_f32_e64 v56, v220, v56
	v_add_f32_e64 v57, v221, v57
	ds_read_b128 v[124:127], v216 offset:1984
	v_pk_add_f32 v[84:85], v[240:241], v[56:57]
	v_mfma_f32_16x16x32_bf16 v[56:59], v[140:143], v[52:55], v[120:123]
	v_add_f32_e64 v52, v242, v84
	v_add_f32_e64 v53, v243, v85
	v_pk_add_f32 v[52:53], v[236:237], v[52:53]
	s_waitcnt lgkmcnt(0)
	v_mfma_f32_16x16x32_bf16 v[84:87], v[132:135], v[124:127], v[116:119]
	v_add_f32_e64 v52, v238, v52
	v_add_f32_e64 v53, v239, v53
	v_pk_add_f32 v[52:53], v[244:245], v[52:53]
	s_nop 0
	v_pk_add_f32 v[52:53], v[246:247], v[52:53]
	s_nop 0
	v_pk_fma_f32 v[190:191], v[190:191], v[2:3], v[52:53]
	v_mfma_f32_16x16x32_bf16 v[52:55], v[140:143], v[124:127], v[128:131]
	s_add_i32 s77, s77, 1
	s_cmp_eq_u32 s82, s77
	v_add_u32_e32 v234, 0x80, v234
	s_barrier
	s_cbranch_scc1 .LBB0_712
.LBB0_708:
	s_and_b32 s0, s77, 1
	s_mul_i32 s67, s0, 0x4400
	s_xor_b32 s0, s0, 1
	s_mul_i32 s0, s0, 0x8800
	v_add_u32_e32 v2, s0, v230
	s_waitcnt vmcnt(7)
	ds_write_b128 v2, v[20:23]
	s_waitcnt vmcnt(6)
	ds_write_b128 v2, v[24:27] offset:8704
	s_waitcnt vmcnt(5)
	ds_write_b128 v2, v[28:31] offset:17408
	s_waitcnt vmcnt(4)
	ds_write_b128 v2, v[32:35] offset:26112
	s_mov_b32 s98, 0x11000
	v_and_b32_e32 v20, 15, v181
	v_bfe_u32 v21, v181, 4, 4
	v_not_b32_e32 v23, v21
	v_and_b32_e32 v23, 1, v23
	v_lshlrev_b32_e32 v23, 1, v23
	v_add_u32_e32 v24, 4, v21
	v_bfe_u32 v24, v24, 3, 1
	v_or_b32_e32 v23, v23, v24
	v_xor_b32_e32 v22, v20, v23
	v_lshlrev_b32_e32 v22, 4, v22
	v_sub_u32_e32 v22, v2, v22
	v_add_u32_e32 v22, s98, v22
	v_lshrrev_b32_e32 v24, 2, v20
	v_lshl_add_u32 v22, v24, 6, v22
	v_bfe_u32 v24, v20, 1, 1
	v_lshl_add_u32 v22, v24, 3, v22
	v_and_b32_e32 v24, 1, v20
	v_lshlrev_b32_e32 v24, 1, v24
	v_xor_b32_e32 v24, v24, v23
	v_xor_b32_e32 v23, 1, v24
	v_lshl_add_u32 v3, v24, 4, v22
	v_lshl_add_u32 v25, v23, 4, v22
	s_waitcnt vmcnt(3)
	ds_write_b64 v3, v[36:37]
	ds_write_b64 v25, v[38:39]
	s_waitcnt vmcnt(2)
	ds_write_b64 v3, v[40:41] offset:8704
	ds_write_b64 v25, v[42:43] offset:8704
	v_lshl_add_u32 v0, s67, 1, v231
	s_waitcnt vmcnt(1)
	ds_write_b64 v3, v[44:45] offset:17408
	ds_write_b64 v25, v[46:47] offset:17408
	s_waitcnt vmcnt(0)
; #define MFMA(a, b, c) __builtin_amdgcn_mfma_f32_16x16x32_bf16(a, b, c, 0, 0, 0)
; DEV void attn_item(const Params& p, int layer, int h, int qb, float lam, bf16_t* lds) {
;     ...
;   for (int kb = 0; kb <= qb; kb++) {
;     const int cur = kb & 1;
;     const bf16_t* kp = KV + cur * TS + lr * PS + grp * 64 + lg * 8;
;     const bf16_t* vq = KV + 2 * TS + cur * TS + lr * PS + lg * 4;
;     {
;       bf16_t* sp = KV + (cur ^ 1) * TS + lrow * PS + lc8;
;       ASTORE(sp)
;     }
;     __builtin_amdgcn_sched_barrier(0);
;     f32x4 s[2][8];
;     {
; #pragma unroll
;       for (int j = 0; j < 8; j++) {
;         const bf16x8 kf0 = *(const bf16x8*)(kp + j * 16 * PS);
;         const bf16x8 kf1 = *(const bf16x8*)(kp + j * 16 * PS + 32);
;         s[0][j] = MFMA(kf0, a00, ((f32x4){0.f, 0.f, 0.f, 0.f}));
;         s[1][j] = MFMA(kf0, a10, ((f32x4){0.f, 0.f, 0.f, 0.f}));
;         s[0][j] = MFMA(kf1, a01, s[0][j]);
;         s[1][j] = MFMA(kf1, a11, s[1][j]);
;       }
;     }
;     __builtin_amdgcn_sched_barrier(0);
;     {
;       const int kbn = (kb + 2 <= qb) ? kb + 2 : qb;
;       ALOAD(kbn)
;     }
;     __builtin_amdgcn_sched_barrier(0);
	ds_write_b64 v3, v[48:49] offset:26112
	ds_write_b64 v25, v[50:51] offset:26112
	ds_read_b128 v[20:23], v0
	ds_read_b128 v[24:27], v0 offset:64
	ds_read_b128 v[32:35], v0 offset:4352
	ds_read_b128 v[36:39], v0 offset:4416
	ds_read_b128 v[40:43], v0 offset:8704
	ds_read_b128 v[44:47], v0 offset:8768
	s_waitcnt lgkmcnt(4)
	v_mfma_f32_16x16x32_bf16 v[176:179], v[20:23], v[4:7], 0
	v_mfma_f32_16x16x32_bf16 v[168:171], v[20:23], v[12:15], 0
	v_mfma_f32_16x16x32_bf16 v[176:179], v[24:27], v[8:11], v[176:179]
	v_mfma_f32_16x16x32_bf16 v[168:171], v[24:27], v[16:19], v[168:171]
	ds_read_b128 v[20:23], v0 offset:13056
	ds_read_b128 v[24:27], v0 offset:13120
	s_waitcnt lgkmcnt(4)
	v_mfma_f32_16x16x32_bf16 v[172:175], v[32:35], v[4:7], 0
	v_mfma_f32_16x16x32_bf16 v[164:167], v[32:35], v[12:15], 0
	v_mfma_f32_16x16x32_bf16 v[172:175], v[36:39], v[8:11], v[172:175]
	v_mfma_f32_16x16x32_bf16 v[164:167], v[36:39], v[16:19], v[164:167]
	ds_read_b128 v[32:35], v0 offset:17408
	ds_read_b128 v[36:39], v0 offset:17472
	s_waitcnt lgkmcnt(4)
	v_mfma_f32_16x16x32_bf16 v[160:163], v[40:43], v[4:7], 0
	v_mfma_f32_16x16x32_bf16 v[152:155], v[40:43], v[12:15], 0
	v_mfma_f32_16x16x32_bf16 v[160:163], v[44:47], v[8:11], v[160:163]
	v_mfma_f32_16x16x32_bf16 v[152:155], v[44:47], v[16:19], v[152:155]
	ds_read_b128 v[40:43], v0 offset:21760
	ds_read_b128 v[44:47], v0 offset:21824
	s_waitcnt lgkmcnt(4)
	v_mfma_f32_16x16x32_bf16 v[156:159], v[20:23], v[4:7], 0
	v_mfma_f32_16x16x32_bf16 v[148:151], v[20:23], v[12:15], 0
	v_mfma_f32_16x16x32_bf16 v[156:159], v[24:27], v[8:11], v[156:159]
	v_mfma_f32_16x16x32_bf16 v[148:151], v[24:27], v[16:19], v[148:151]
	ds_read_b128 v[20:23], v0 offset:26112
	ds_read_b128 v[24:27], v0 offset:26176
	s_waitcnt lgkmcnt(4)
	v_mfma_f32_16x16x32_bf16 v[144:147], v[32:35], v[4:7], 0
	v_mfma_f32_16x16x32_bf16 v[136:139], v[32:35], v[12:15], 0
	v_mfma_f32_16x16x32_bf16 v[144:147], v[36:39], v[8:11], v[144:147]
	v_mfma_f32_16x16x32_bf16 v[136:139], v[36:39], v[16:19], v[136:139]
	ds_read_b128 v[32:35], v0 offset:30464
	ds_read_b128 v[36:39], v0 offset:30528
	s_waitcnt lgkmcnt(4)
	v_mfma_f32_16x16x32_bf16 v[140:143], v[40:43], v[4:7], 0
	v_mfma_f32_16x16x32_bf16 v[132:135], v[40:43], v[12:15], 0
	v_mfma_f32_16x16x32_bf16 v[140:143], v[44:47], v[8:11], v[140:143]
	v_mfma_f32_16x16x32_bf16 v[132:135], v[44:47], v[16:19], v[132:135]
	s_waitcnt lgkmcnt(2)
	v_mfma_f32_16x16x32_bf16 v[128:131], v[20:23], v[4:7], 0
	v_mfma_f32_16x16x32_bf16 v[120:123], v[20:23], v[12:15], 0
	v_mfma_f32_16x16x32_bf16 v[128:131], v[24:27], v[8:11], v[128:131]
	v_mfma_f32_16x16x32_bf16 v[120:123], v[24:27], v[16:19], v[120:123]
	s_waitcnt lgkmcnt(0)
	v_mfma_f32_16x16x32_bf16 v[124:127], v[32:35], v[4:7], 0
	v_mfma_f32_16x16x32_bf16 v[116:119], v[32:35], v[12:15], 0
	v_mfma_f32_16x16x32_bf16 v[124:127], v[36:39], v[8:11], v[124:127]
	v_mfma_f32_16x16x32_bf16 v[116:119], v[36:39], v[16:19], v[116:119]
	s_nop 0
	s_add_i32 s0, s77, 2
	s_min_u32 s0, s0, s76
	v_lshl_add_u32 v0, s0, 17, v186
	s_nop 1
	v_add_u32_e32 v20, 0x8000, v0
	v_mov_b32_e32 v21, v1
	v_lshl_add_u64 v[2:3], v[0:1], 1, s[78:79]
	v_lshl_add_u64 v[24:25], v[20:21], 1, s[78:79]
	global_load_dwordx4 v[20:23], v[2:3], off
	s_nop 0
	global_load_dwordx4 v[24:27], v[24:25], off
	v_add_u32_e32 v2, 0x10000, v0
	v_add_u32_e32 v0, 0x18000, v0
	v_mov_b32_e32 v3, v1
	v_lshl_add_u64 v[32:33], v[0:1], 1, s[78:79]
	v_lshl_add_u32 v0, s0, 7, v188
	v_lshl_add_u64 v[2:3], v[2:3], 1, s[78:79]
	v_add_u32_e32 v36, 0x41000, v0
	v_mov_b32_e32 v37, v1
	global_load_dwordx4 v[28:31], v[2:3], off
	s_nop 0
	global_load_dwordx4 v[32:35], v[32:33], off
	v_lshl_add_u64 v[2:3], v[0:1], 1, s[70:71]
	v_lshl_add_u64 v[40:41], v[36:37], 1, s[70:71]
	global_load_dwordx4 v[36:39], v[2:3], off
	s_nop 0
	global_load_dwordx4 v[40:43], v[40:41], off
	v_add_u32_e32 v2, 0x82000, v0
	v_mov_b32_e32 v3, v1
	v_add_u32_e32 v0, 0xc3000, v0
	v_lshl_add_u64 v[2:3], v[2:3], 1, s[70:71]
	v_lshl_add_u64 v[48:49], v[0:1], 1, s[70:71]
	global_load_dwordx4 v[44:47], v[2:3], off
	s_nop 0
	global_load_dwordx4 v[48:51], v[48:49], off
	s_cmp_lg_u32 s76, s77
	s_cselect_b64 s[0:1], -1, 0
	s_cmp_eq_u32 s77, 0
	s_cselect_b64 s[2:3], -1, 0
	s_cmp_lg_u32 s77, 0
	s_cselect_b64 s[6:7], -1, 0
	s_and_b64 s[0:1], s[0:1], s[6:7]
	s_and_b64 vcc, exec, s[0:1]
	s_cbranch_vccnz .LBB0_710
; DEV void attn_item(const Params& p, int layer, int h, int qb, float lam, bf16_t* lds) {
;     ...
;     if (kb == qb || kb == 0) {
; #pragma unroll
;       for (int i = 0; i < 2; i++)
; #pragma unroll
;         for (int j = 0; j < 8; j++)
; #pragma unroll
;           for (int r = 0; r < 4; r++) {
;             const int key = kb * 128 + j * 16 + lg * 4 + r;
;             if (key > qrow0 + 16 * i || key < 112) s[i][j][r] = -1e30f;
;           }
;     }
	v_cmp_gt_u32_e32 vcc, v234, v184
	v_mov_b32_e32 v0, s68
	s_or_b64 s[0:1], s[2:3], vcc
	v_cndmask_b32_e64 v176, v176, v0, s[0:1]
	v_cmp_ge_u32_e64 s[0:1], v234, v184
	s_or_b64 s[0:1], s[2:3], s[0:1]
	v_add_u32_e32 v2, 2, v234
	v_cndmask_b32_e64 v177, v177, v219, s[0:1]
	v_cmp_gt_u32_e64 s[0:1], v2, v184
	s_or_b64 s[0:1], s[2:3], s[0:1]
	v_add_u32_e32 v3, 3, v234
	v_cndmask_b32_e64 v178, v178, v219, s[0:1]
	v_cmp_gt_u32_e64 s[0:1], v3, v184
	s_or_b64 s[0:1], s[2:3], s[0:1]
	v_add_u32_e32 v0, 16, v234
	v_cndmask_b32_e64 v179, v179, v219, s[0:1]
	v_cmp_gt_u32_e64 s[0:1], v0, v184
	v_cmp_gt_u32_e64 s[6:7], s61, v0
	v_mov_b32_e32 v0, s68
	s_or_b64 s[0:1], s[0:1], s[6:7]
	v_add_u32_e32 v194, 17, v234
	v_cndmask_b32_e64 v172, v172, v0, s[0:1]
	v_cmp_gt_u32_e64 s[0:1], v194, v184
	v_cmp_gt_u32_e64 s[8:9], s61, v194
	s_or_b64 s[0:1], s[0:1], s[8:9]
	v_add_u32_e32 v195, 18, v234
	v_cndmask_b32_e64 v173, v173, v219, s[0:1]
	v_cmp_gt_u32_e64 s[0:1], v195, v184
	v_cmp_gt_u32_e64 s[10:11], s61, v195
	s_or_b64 s[0:1], s[0:1], s[10:11]
	v_add_u32_e32 v196, 19, v234
	v_cndmask_b32_e64 v174, v174, v219, s[0:1]
	v_cmp_gt_u32_e64 s[0:1], v196, v184
	v_cmp_gt_u32_e64 s[12:13], s61, v196
	s_or_b64 s[0:1], s[0:1], s[12:13]
	v_add_u32_e32 v197, 32, v234
	v_cndmask_b32_e64 v175, v175, v219, s[0:1]
	v_cmp_gt_u32_e64 s[0:1], v197, v184
	v_cmp_gt_u32_e64 s[14:15], s61, v197
	s_or_b64 s[0:1], s[0:1], s[14:15]
	v_add_u32_e32 v198, 33, v234
	s_or_b64 vcc, vcc, s[6:7]
	v_cndmask_b32_e64 v160, v160, v0, s[0:1]
	v_cmp_gt_u32_e64 s[0:1], v198, v184
	v_cmp_gt_u32_e64 s[16:17], s61, v198
	v_cndmask_b32_e32 v164, v164, v0, vcc
	v_cmp_gt_u32_e32 vcc, v194, v233
	s_or_b64 s[0:1], s[0:1], s[16:17]
	v_add_u32_e32 v199, 34, v234
	s_or_b64 vcc, vcc, s[8:9]
	v_cndmask_b32_e64 v161, v161, v219, s[0:1]
	v_cmp_gt_u32_e64 s[0:1], v199, v184
	v_cmp_gt_u32_e64 s[18:19], s61, v199
	v_cndmask_b32_e32 v165, v165, v219, vcc
	v_cmp_gt_u32_e32 vcc, v195, v233
	s_or_b64 s[0:1], s[0:1], s[18:19]
	v_add_u32_e32 v200, 35, v234
	s_or_b64 vcc, vcc, s[10:11]
	v_cndmask_b32_e64 v162, v162, v219, s[0:1]
	v_cmp_gt_u32_e64 s[0:1], v200, v184
	v_cmp_gt_u32_e64 s[20:21], s61, v200
	v_cndmask_b32_e32 v166, v166, v219, vcc
	v_cmp_gt_u32_e32 vcc, v196, v233
	s_or_b64 s[0:1], s[0:1], s[20:21]
	v_add_u32_e32 v201, 48, v234
	s_or_b64 vcc, vcc, s[12:13]
	v_cndmask_b32_e64 v163, v163, v219, s[0:1]
	v_cmp_gt_u32_e64 s[0:1], v201, v184
	v_cmp_gt_u32_e64 s[22:23], s61, v201
	v_cndmask_b32_e32 v167, v167, v219, vcc
	v_cmp_gt_u32_e32 vcc, v197, v233
	s_or_b64 s[0:1], s[0:1], s[22:23]
	v_add_u32_e32 v202, 49, v234
	s_or_b64 vcc, vcc, s[14:15]
	v_cndmask_b32_e64 v156, v156, v0, s[0:1]
	v_cmp_gt_u32_e64 s[0:1], v202, v184
	v_cmp_gt_u32_e64 s[24:25], s61, v202
	v_cndmask_b32_e32 v152, v152, v0, vcc
	v_cmp_gt_u32_e32 vcc, v198, v233
	s_or_b64 s[0:1], s[0:1], s[24:25]
	v_add_u32_e32 v203, 50, v234
	s_or_b64 vcc, vcc, s[16:17]
	v_cndmask_b32_e64 v157, v157, v219, s[0:1]
	v_cmp_gt_u32_e64 s[0:1], v203, v184
	v_cmp_gt_u32_e64 s[26:27], s61, v203
	v_cndmask_b32_e32 v153, v153, v219, vcc
	v_cmp_gt_u32_e32 vcc, v199, v233
	s_or_b64 s[0:1], s[0:1], s[26:27]
	v_add_u32_e32 v208, 51, v234
	s_or_b64 vcc, vcc, s[18:19]
	v_cndmask_b32_e64 v158, v158, v219, s[0:1]
	v_cmp_gt_u32_e64 s[0:1], v208, v184
	v_cmp_gt_u32_e64 s[28:29], s61, v208
	v_cndmask_b32_e32 v154, v154, v219, vcc
	v_cmp_gt_u32_e32 vcc, v200, v233
	s_or_b64 s[0:1], s[0:1], s[28:29]
	v_add_u32_e32 v209, 64, v234
	s_or_b64 vcc, vcc, s[20:21]
	v_cndmask_b32_e64 v159, v159, v219, s[0:1]
	v_cmp_gt_u32_e64 s[0:1], v209, v184
	v_cmp_gt_u32_e64 s[30:31], s61, v209
	v_cndmask_b32_e32 v155, v155, v219, vcc
	v_cmp_gt_u32_e32 vcc, v201, v233
	s_or_b64 s[0:1], s[0:1], s[30:31]
	v_add_u32_e32 v210, 0x41, v234
	s_or_b64 vcc, vcc, s[22:23]
	v_cndmask_b32_e64 v144, v144, v0, s[0:1]
	v_cmp_gt_u32_e64 s[0:1], v210, v184
	v_cmp_gt_u32_e64 s[34:35], s61, v210
	v_cndmask_b32_e32 v148, v148, v0, vcc
	v_cmp_gt_u32_e32 vcc, v202, v233
	s_or_b64 s[0:1], s[0:1], s[34:35]
	v_add_u32_e32 v211, 0x42, v234
	s_or_b64 vcc, vcc, s[24:25]
	v_cndmask_b32_e64 v145, v145, v219, s[0:1]
	v_cmp_gt_u32_e64 s[0:1], v211, v184
	v_cmp_gt_u32_e64 s[36:37], s61, v211
	v_cndmask_b32_e32 v149, v149, v219, vcc
	v_cmp_gt_u32_e32 vcc, v203, v233
	s_or_b64 s[0:1], s[0:1], s[36:37]
	v_add_u32_e32 v220, 0x43, v234
	s_or_b64 vcc, vcc, s[26:27]
	v_cndmask_b32_e64 v146, v146, v219, s[0:1]
; DEV void attn_item(const Params& p, int layer, int h, int qb, float lam, bf16_t* lds) {
;     ...
;     if (kb == qb || kb == 0) {
; #pragma unroll
;       for (int i = 0; i < 2; i++)
; #pragma unroll
;         for (int j = 0; j < 8; j++)
; #pragma unroll
;           for (int r = 0; r < 4; r++) {
;             const int key = kb * 128 + j * 16 + lg * 4 + r;
;             if (key > qrow0 + 16 * i || key < 112) s[i][j][r] = -1e30f;
;           }
;     }
	v_cmp_gt_u32_e64 s[0:1], v220, v184
	v_cmp_gt_u32_e64 s[38:39], s61, v220
	v_cndmask_b32_e32 v150, v150, v219, vcc
	v_cmp_gt_u32_e32 vcc, v208, v233
	s_or_b64 s[0:1], s[0:1], s[38:39]
	v_add_u32_e32 v221, 0x50, v234
	s_or_b64 vcc, vcc, s[28:29]
	v_cndmask_b32_e64 v147, v147, v219, s[0:1]
	v_cmp_gt_u32_e64 s[0:1], v221, v184
	v_cmp_gt_u32_e64 s[40:41], s61, v221
	v_cndmask_b32_e32 v151, v151, v219, vcc
	v_cmp_gt_u32_e32 vcc, v209, v233
	s_or_b64 s[0:1], s[0:1], s[40:41]
	v_add_u32_e32 v236, 0x51, v234
	s_or_b64 vcc, vcc, s[30:31]
	v_cndmask_b32_e64 v140, v140, v0, s[0:1]
	v_cmp_gt_u32_e64 s[0:1], v236, v184
	v_cmp_gt_u32_e64 s[42:43], s61, v236
	v_cndmask_b32_e32 v136, v136, v0, vcc
	v_cmp_gt_u32_e32 vcc, v210, v233
	s_or_b64 s[0:1], s[0:1], s[42:43]
	v_add_u32_e32 v237, 0x52, v234
	s_or_b64 vcc, vcc, s[34:35]
	v_cndmask_b32_e64 v141, v141, v219, s[0:1]
	v_cmp_gt_u32_e64 s[0:1], v237, v184
	v_cmp_gt_u32_e64 s[44:45], s61, v237
	v_cndmask_b32_e32 v137, v137, v219, vcc
	v_cmp_gt_u32_e32 vcc, v211, v233
	s_or_b64 s[0:1], s[0:1], s[44:45]
	v_add_u32_e32 v238, 0x53, v234
	s_or_b64 vcc, vcc, s[36:37]
	v_cndmask_b32_e64 v142, v142, v219, s[0:1]
	v_cmp_gt_u32_e64 s[0:1], v238, v184
	v_cmp_gt_u32_e64 s[46:47], s61, v238
	v_cndmask_b32_e32 v138, v138, v219, vcc
	v_cmp_gt_u32_e32 vcc, v220, v233
	s_or_b64 s[0:1], s[0:1], s[46:47]
	v_add_u32_e32 v239, 0x60, v234
	s_or_b64 vcc, vcc, s[38:39]
	v_cndmask_b32_e64 v143, v143, v219, s[0:1]
	v_cmp_gt_u32_e64 s[0:1], v239, v184
	v_cmp_gt_u32_e64 s[48:49], s61, v239
	v_cndmask_b32_e32 v139, v139, v219, vcc
	v_cmp_gt_u32_e32 vcc, v221, v233
	s_or_b64 s[0:1], s[0:1], s[48:49]
	v_add_u32_e32 v240, 0x61, v234
	s_or_b64 vcc, vcc, s[40:41]
	v_cndmask_b32_e64 v128, v128, v0, s[0:1]
	v_cmp_gt_u32_e64 s[52:53], v240, v184
	v_cmp_gt_u32_e64 s[0:1], s61, v240
	v_cndmask_b32_e32 v132, v132, v0, vcc
	v_cmp_gt_u32_e32 vcc, v236, v233
	s_or_b64 s[52:53], s[52:53], s[0:1]
	v_add_u32_e32 v241, 0x62, v234
	s_or_b64 vcc, vcc, s[42:43]
	v_cndmask_b32_e64 v129, v129, v219, s[52:53]
	v_cmp_gt_u32_e64 s[54:55], v241, v184
	v_cmp_gt_u32_e64 s[52:53], s61, v241
	v_cndmask_b32_e32 v133, v133, v219, vcc
	v_cmp_gt_u32_e32 vcc, v237, v233
	s_or_b64 s[54:55], s[54:55], s[52:53]
	v_add_u32_e32 v242, 0x63, v234
	s_or_b64 vcc, vcc, s[44:45]
	v_cndmask_b32_e64 v130, v130, v219, s[54:55]
	v_cmp_gt_u32_e64 s[58:59], v242, v184
	v_cmp_gt_u32_e64 s[54:55], s61, v242
	v_cndmask_b32_e32 v134, v134, v219, vcc
	v_cmp_gt_u32_e32 vcc, v238, v233
	s_or_b64 s[58:59], s[58:59], s[54:55]
	v_add_u32_e32 v243, 0x70, v234
	s_or_b64 vcc, vcc, s[46:47]
	v_cndmask_b32_e64 v131, v131, v219, s[58:59]
	v_cmp_gt_u32_e64 s[58:59], v243, v184
	v_add_u32_e32 v244, 0x71, v234
	v_cndmask_b32_e32 v135, v135, v219, vcc
	v_cmp_gt_u32_e32 vcc, v239, v233
	v_cndmask_b32_e64 v124, v124, v0, s[58:59]
	v_cmp_le_u32_e64 s[58:59], v244, v184
	v_add_u32_e32 v245, 0x72, v234
	s_or_b64 vcc, vcc, s[48:49]
	v_cndmask_b32_e64 v125, v219, v125, s[58:59]
	v_cmp_le_u32_e64 s[58:59], v245, v184
	v_add_u32_e32 v246, 0x73, v234
	v_cndmask_b32_e32 v120, v120, v0, vcc
	v_cmp_gt_u32_e32 vcc, v240, v233
	v_cndmask_b32_e64 v126, v219, v126, s[58:59]
	v_cmp_le_u32_e64 s[58:59], v246, v184
	s_or_b64 vcc, vcc, s[0:1]
	v_cndmask_b32_e32 v121, v121, v219, vcc
	v_cndmask_b32_e64 v127, v219, v127, s[58:59]
	v_cmp_gt_u32_e64 s[58:59], v234, v233
	v_cmp_gt_u32_e32 vcc, v241, v233
	s_or_b64 s[58:59], s[2:3], s[58:59]
	s_or_b64 vcc, vcc, s[52:53]
	v_cndmask_b32_e64 v168, v168, v0, s[58:59]
	v_cmp_ge_u32_e64 s[58:59], v234, v233
	v_cndmask_b32_e32 v122, v122, v219, vcc
	v_cmp_gt_u32_e32 vcc, v242, v233
	s_or_b64 s[58:59], s[2:3], s[58:59]
	s_or_b64 vcc, vcc, s[54:55]
	v_cndmask_b32_e64 v169, v169, v219, s[58:59]
	v_cmp_gt_u32_e64 s[58:59], v2, v233
	v_cndmask_b32_e32 v123, v123, v219, vcc
	v_cmp_gt_u32_e32 vcc, v243, v233
	s_or_b64 s[58:59], s[2:3], s[58:59]
	v_cndmask_b32_e64 v170, v170, v219, s[58:59]
	v_cndmask_b32_e32 v116, v116, v0, vcc
	v_cmp_le_u32_e32 vcc, v244, v233
	v_cmp_gt_u32_e64 s[58:59], v3, v233
	s_or_b64 s[58:59], s[2:3], s[58:59]
	v_cndmask_b32_e32 v117, v219, v117, vcc
	v_cmp_le_u32_e32 vcc, v245, v233
	v_cndmask_b32_e64 v171, v171, v219, s[58:59]
	s_movk_i32 s31, 0x207f
	v_cndmask_b32_e32 v118, v219, v118, vcc
	v_cmp_le_u32_e32 vcc, v246, v233
	s_mov_b32 s30, 0x800000
	s_mov_b32 s39, s74
	v_cndmask_b32_e32 v119, v219, v119, vcc
